# global attention: all tiles in hand loop with dedicated final iteration (no remainder loop, no over-reads beyond one K tile)
# speedup vs baseline: 1.0087x; 1.0087x over previous
.Lattn_main:
	s_mov_b32 s84, s7
	s_waitcnt lgkmcnt(7)
	v_mfma_f32_32x32x16_bf16 v[64:79], v[222:225], v[96:99], 0
	ds_read_b128 v[222:225], v186 offset:36864
	v_add_f32_e32 v188, v188, v32
	v_add_f32_e32 v189, v189, v33
	v_cvt_pk_bf16_f32 v32, v32, v33
	v_add_f32_e32 v190, v190, v34
	v_add_f32_e32 v191, v191, v35
	v_cvt_pk_bf16_f32 v33, v34, v35
	v_exp_f32_e32 v48, v48
	v_exp_f32_e32 v49, v49
	s_waitcnt lgkmcnt(7)
	v_mfma_f32_32x32x16_bf16 v[206:221], v[226:229], v[96:99], 0
	ds_read_b128 v[226:229], v186 offset:41472
	v_add_f32_e32 v192, v192, v36
	v_add_f32_e32 v193, v193, v37
	v_cvt_pk_bf16_f32 v34, v36, v37
	v_exp_f32_e32 v50, v50
	v_exp_f32_e32 v51, v51
	s_waitcnt lgkmcnt(7)
	v_mfma_f32_32x32x16_bf16 v[64:79], v[230:233], v[100:103], v[64:79]
	ds_read_b128 v[230:233], v186 offset:36896
	v_add_f32_e32 v194, v194, v38
	v_add_f32_e32 v195, v195, v39
	v_cvt_pk_bf16_f32 v35, v38, v39
	v_exp_f32_e32 v52, v52
	v_exp_f32_e32 v53, v53
	s_waitcnt lgkmcnt(7)
	v_mfma_f32_32x32x16_bf16 v[206:221], v[234:237], v[100:103], v[206:221]
	ds_read_b128 v[234:237], v186 offset:41504
	v_add_f32_e32 v196, v196, v40
	v_add_f32_e32 v197, v197, v41
	v_cvt_pk_bf16_f32 v36, v40, v41
	v_exp_f32_e32 v54, v54
	v_exp_f32_e32 v55, v55
	s_waitcnt lgkmcnt(7)
	v_mfma_f32_32x32x16_bf16 v[64:79], v[138:141], v[104:107], v[64:79]
	ds_read_b128 v[138:141], v186 offset:36928
	v_add_f32_e32 v198, v198, v42
	v_add_f32_e32 v199, v199, v43
	v_cvt_pk_bf16_f32 v37, v42, v43
	v_exp_f32_e32 v56, v56
	v_exp_f32_e32 v57, v57
	s_waitcnt lgkmcnt(7)
	v_mfma_f32_32x32x16_bf16 v[206:221], v[142:145], v[104:107], v[206:221]
	ds_read_b128 v[142:145], v186 offset:41536
	v_add_f32_e32 v200, v200, v44
	v_add_f32_e32 v201, v201, v45
	v_cvt_pk_bf16_f32 v38, v44, v45
	v_exp_f32_e32 v58, v58
	v_exp_f32_e32 v59, v59
	s_waitcnt lgkmcnt(7)
	v_mfma_f32_32x32x16_bf16 v[64:79], v[162:165], v[108:111], v[64:79]
	ds_read_b128 v[162:165], v186 offset:36960
	v_add_f32_e32 v202, v202, v46
	v_add_f32_e32 v203, v203, v47
	v_cvt_pk_bf16_f32 v39, v46, v47
	v_exp_f32_e32 v60, v60
	v_exp_f32_e32 v61, v61
	s_waitcnt lgkmcnt(7)
	v_mfma_f32_32x32x16_bf16 v[206:221], v[132:135], v[108:111], v[206:221]
	ds_read_b128 v[132:135], v186 offset:41568
	v_add_f32_e32 v188, v188, v48
	v_add_f32_e32 v189, v189, v49
	v_cvt_pk_bf16_f32 v48, v48, v49
	v_add_f32_e32 v190, v190, v50
	v_add_f32_e32 v191, v191, v51
	v_cvt_pk_bf16_f32 v49, v50, v51
	v_exp_f32_e32 v62, v62
	v_exp_f32_e32 v63, v63
	s_waitcnt lgkmcnt(7)
	v_mfma_f32_32x32x16_bf16 v[0:15], v[222:225], v[32:35], v[0:15]
	ds_read_b128 v[222:225], v186 offset:18432
	v_add_f32_e32 v192, v192, v52
	v_add_f32_e32 v193, v193, v53
	v_cvt_pk_bf16_f32 v50, v52, v53
	v_exp_f32_e32 v64, v64
	v_exp_f32_e32 v65, v65
	s_waitcnt lgkmcnt(7)
	v_mfma_f32_32x32x16_bf16 v[16:31], v[226:229], v[32:35], v[16:31]
	ds_read_b128 v[226:229], v186 offset:23040
	v_add_f32_e32 v194, v194, v54
	v_add_f32_e32 v195, v195, v55
	v_cvt_pk_bf16_f32 v51, v54, v55
	v_exp_f32_e32 v66, v66
	v_exp_f32_e32 v67, v67
	s_waitcnt lgkmcnt(7)
	v_mfma_f32_32x32x16_bf16 v[0:15], v[230:233], v[36:39], v[0:15]
	ds_read_b128 v[230:233], v186 offset:18464
	v_add_f32_e32 v196, v196, v56
	v_add_f32_e32 v197, v197, v57
	v_cvt_pk_bf16_f32 v52, v56, v57
	v_exp_f32_e32 v68, v68
	v_exp_f32_e32 v69, v69
	v_add_u32_e32 v204, 0xd800, v136
	v_add_u32_e32 v205, 0xf800, v136
	s_waitcnt vmcnt(3)
	ds_write_b128 v168, v[112:115] offset:27648
	s_waitcnt vmcnt(2)
	s_waitcnt lgkmcnt(8)
	v_mfma_f32_32x32x16_bf16 v[16:31], v[234:237], v[36:39], v[16:31]
	ds_read_b128 v[234:237], v186 offset:23072
	v_add_f32_e32 v198, v198, v58
	v_add_f32_e32 v199, v199, v59
	v_cvt_pk_bf16_f32 v53, v58, v59
	v_exp_f32_e32 v70, v70
	v_exp_f32_e32 v71, v71
	ds_write_b128 v168, v[116:119]
	s_waitcnt vmcnt(1)
	ds_write2_b64 v204, v[120:121], v[122:123] offset1:2
	s_waitcnt vmcnt(0)
	ds_write2_b64 v205, v[124:125], v[126:127] offset0:128 offset1:130
	s_waitcnt lgkmcnt(11)
	v_mfma_f32_32x32x16_bf16 v[0:15], v[138:141], v[48:51], v[0:15]
	ds_read_b128 v[138:141], v186 offset:18496
	v_add_f32_e32 v200, v200, v60
	v_add_f32_e32 v201, v201, v61
	v_cvt_pk_bf16_f32 v54, v60, v61
	v_exp_f32_e32 v72, v72
	v_exp_f32_e32 v73, v73
	v_lshl_add_u64 v[120:121], v[128:129], 0, v[150:151]
	v_lshl_add_u64 v[124:125], v[130:131], 0, v[150:151]
	s_mov_b32 s98, 0xd8c8000
	v_lshl_add_u64 v[146:147], v[120:121], 0, s[98:99]
	global_load_dwordx4 v[80:83], v[146:147], off offset:2304
	s_waitcnt lgkmcnt(11)
	v_mfma_f32_32x32x16_bf16 v[16:31], v[142:145], v[48:51], v[16:31]
	ds_read_b128 v[142:145], v186 offset:23104
	v_add_f32_e32 v202, v202, v62
	v_add_f32_e32 v203, v203, v63
	v_cvt_pk_bf16_f32 v55, v62, v63
	v_exp_f32_e32 v74, v74
	v_exp_f32_e32 v75, v75
	s_mov_b32 s98, 0xd8f0000
	v_lshl_add_u64 v[146:147], v[120:121], 0, s[98:99]
	global_load_dwordx4 v[84:87], v[146:147], off offset:2304
	s_mov_b32 s98, 0x17820000
	v_lshl_add_u64 v[146:147], v[124:125], 0, s[98:99]
	s_waitcnt lgkmcnt(11)
	v_mfma_f32_32x32x16_bf16 v[0:15], v[162:165], v[52:55], v[0:15]
	ds_read_b128 v[162:165], v186 offset:18528
	v_exp_f32_e32 v76, v76
	v_exp_f32_e32 v77, v77
	global_load_dwordx4 v[88:91], v[146:147], off
	s_mov_b32 s98, 0x17828000
	v_lshl_add_u64 v[146:147], v[124:125], 0, s[98:99]
	global_load_dwordx4 v[92:95], v[146:147], off
	v_lshl_add_u64 v[128:129], v[128:129], 0, s[26:27]
	s_waitcnt lgkmcnt(11)
	v_mfma_f32_32x32x16_bf16 v[16:31], v[132:135], v[52:55], v[16:31]
	ds_read_b128 v[132:135], v186 offset:23136
	v_exp_f32_e32 v78, v78
	v_exp_f32_e32 v79, v79
	v_lshl_add_u64 v[130:131], v[130:131], 0, s[28:29]
	s_mov_b32 s14, s8
	s_add_i32 s6, s6, 4
	s_add_i32 s8, s8, 4
	s_waitcnt lgkmcnt(11)
	v_mfma_f32_32x32x16_bf16 v[32:47], v[222:225], v[96:99], 0
	ds_read_b128 v[222:225], v186 offset:46080
	v_add_f32_e32 v188, v188, v64
	v_add_f32_e32 v189, v189, v65
	v_cvt_pk_bf16_f32 v64, v64, v65
	v_add_f32_e32 v190, v190, v66
	v_add_f32_e32 v191, v191, v67
	v_cvt_pk_bf16_f32 v65, v66, v67
	v_exp_f32_e32 v206, v206
	v_exp_f32_e32 v207, v207
	s_waitcnt lgkmcnt(11)
	v_mfma_f32_32x32x16_bf16 v[48:63], v[226:229], v[96:99], 0
	ds_read_b128 v[226:229], v186 offset:50688
	v_add_f32_e32 v192, v192, v68
	v_add_f32_e32 v193, v193, v69
	v_cvt_pk_bf16_f32 v66, v68, v69
	v_exp_f32_e32 v208, v208
	v_exp_f32_e32 v209, v209
	s_waitcnt lgkmcnt(11)
	v_mfma_f32_32x32x16_bf16 v[32:47], v[230:233], v[100:103], v[32:47]
	ds_read_b128 v[230:233], v186 offset:46112
	v_add_f32_e32 v194, v194, v70
	v_add_f32_e32 v195, v195, v71
	v_cvt_pk_bf16_f32 v67, v70, v71
	v_exp_f32_e32 v210, v210
	v_exp_f32_e32 v211, v211
	s_waitcnt lgkmcnt(10)
	v_mfma_f32_32x32x16_bf16 v[48:63], v[234:237], v[100:103], v[48:63]
	ds_read_b128 v[234:237], v186 offset:50720
	v_add_f32_e32 v196, v196, v72
	v_add_f32_e32 v197, v197, v73
	v_cvt_pk_bf16_f32 v68, v72, v73
	v_exp_f32_e32 v212, v212
	v_exp_f32_e32 v213, v213
	s_waitcnt lgkmcnt(7)
	v_mfma_f32_32x32x16_bf16 v[32:47], v[138:141], v[104:107], v[32:47]
	ds_read_b128 v[138:141], v186 offset:46144
	v_add_f32_e32 v198, v198, v74
	v_add_f32_e32 v199, v199, v75
	v_cvt_pk_bf16_f32 v69, v74, v75
	v_exp_f32_e32 v214, v214
	v_exp_f32_e32 v215, v215
	s_waitcnt lgkmcnt(7)
	v_mfma_f32_32x32x16_bf16 v[48:63], v[142:145], v[104:107], v[48:63]
	ds_read_b128 v[142:145], v186 offset:50752
	v_add_f32_e32 v200, v200, v76
	v_add_f32_e32 v201, v201, v77
	v_cvt_pk_bf16_f32 v70, v76, v77
	v_exp_f32_e32 v216, v216
	v_exp_f32_e32 v217, v217
	s_waitcnt lgkmcnt(7)
	v_mfma_f32_32x32x16_bf16 v[32:47], v[162:165], v[108:111], v[32:47]
	ds_read_b128 v[162:165], v186 offset:46176
	v_add_f32_e32 v202, v202, v78
	v_add_f32_e32 v203, v203, v79
	v_cvt_pk_bf16_f32 v71, v78, v79
	v_exp_f32_e32 v218, v218
	v_exp_f32_e32 v219, v219
	s_waitcnt lgkmcnt(7)
	v_mfma_f32_32x32x16_bf16 v[48:63], v[132:135], v[108:111], v[48:63]
	ds_read_b128 v[132:135], v186 offset:50784
	v_add_f32_e32 v188, v188, v206
	v_add_f32_e32 v189, v189, v207
	v_cvt_pk_bf16_f32 v206, v206, v207
	v_add_f32_e32 v190, v190, v208
	v_add_f32_e32 v191, v191, v209
	v_cvt_pk_bf16_f32 v207, v208, v209
	v_exp_f32_e32 v220, v220
	v_exp_f32_e32 v221, v221
	s_waitcnt lgkmcnt(7)
	v_mfma_f32_32x32x16_bf16 v[0:15], v[222:225], v[64:67], v[0:15]
	v_add_f32_e32 v192, v192, v210
	v_add_f32_e32 v193, v193, v211
	v_cvt_pk_bf16_f32 v208, v210, v211
	v_exp_f32_e32 v32, v32
	v_exp_f32_e32 v33, v33
	s_waitcnt lgkmcnt(6)
	v_mfma_f32_32x32x16_bf16 v[16:31], v[226:229], v[64:67], v[16:31]
	v_add_f32_e32 v194, v194, v212
	v_add_f32_e32 v195, v195, v213
	v_cvt_pk_bf16_f32 v209, v212, v213
	v_exp_f32_e32 v34, v34
	v_exp_f32_e32 v35, v35
	s_waitcnt lgkmcnt(5)
	v_mfma_f32_32x32x16_bf16 v[0:15], v[230:233], v[68:71], v[0:15]
	v_add_f32_e32 v196, v196, v214
	v_add_f32_e32 v197, v197, v215
	v_cvt_pk_bf16_f32 v210, v214, v215
	v_exp_f32_e32 v36, v36
	v_exp_f32_e32 v37, v37
	s_waitcnt lgkmcnt(4)
	v_mfma_f32_32x32x16_bf16 v[16:31], v[234:237], v[68:71], v[16:31]
	s_waitcnt lgkmcnt(0)
	s_barrier
	ds_read_b128 v[222:225], v186 offset:27648
	ds_read_b128 v[226:229], v186 offset:32256
	ds_read_b128 v[230:233], v186 offset:27680
	ds_read_b128 v[234:237], v186 offset:32288
	v_add_f32_e32 v198, v198, v216
	v_add_f32_e32 v199, v199, v217
	v_cvt_pk_bf16_f32 v211, v216, v217
	v_exp_f32_e32 v38, v38
	v_exp_f32_e32 v39, v39
	v_mfma_f32_32x32x16_bf16 v[0:15], v[138:141], v[206:209], v[0:15]
	ds_read_b128 v[138:141], v186 offset:27712
	v_add_f32_e32 v200, v200, v218
	v_add_f32_e32 v201, v201, v219
	v_cvt_pk_bf16_f32 v212, v218, v219
	v_exp_f32_e32 v40, v40
	v_exp_f32_e32 v41, v41
	v_mfma_f32_32x32x16_bf16 v[16:31], v[142:145], v[206:209], v[16:31]
	ds_read_b128 v[142:145], v186 offset:32320
	v_add_f32_e32 v202, v202, v220
	v_add_f32_e32 v203, v203, v221
	v_cvt_pk_bf16_f32 v213, v220, v221
	v_exp_f32_e32 v42, v42
	v_exp_f32_e32 v43, v43
	v_mfma_f32_32x32x16_bf16 v[0:15], v[162:165], v[210:213], v[0:15]
	ds_read_b128 v[162:165], v186 offset:27744
	v_exp_f32_e32 v44, v44
	v_exp_f32_e32 v45, v45
	v_mfma_f32_32x32x16_bf16 v[16:31], v[132:135], v[210:213], v[16:31]
	ds_read_b128 v[132:135], v186 offset:32352
	v_exp_f32_e32 v46, v46
	v_exp_f32_e32 v47, v47
	s_waitcnt lgkmcnt(7)
	v_mfma_f32_32x32x16_bf16 v[64:79], v[222:225], v[96:99], 0
	ds_read_b128 v[222:225], v186 offset:55296
	v_add_f32_e32 v188, v188, v32
	v_add_f32_e32 v189, v189, v33
	v_cvt_pk_bf16_f32 v32, v32, v33
	v_add_f32_e32 v190, v190, v34
	v_add_f32_e32 v191, v191, v35
	v_cvt_pk_bf16_f32 v33, v34, v35
	v_exp_f32_e32 v48, v48
	v_exp_f32_e32 v49, v49
	s_waitcnt lgkmcnt(7)
	v_mfma_f32_32x32x16_bf16 v[206:221], v[226:229], v[96:99], 0
	ds_read_b128 v[226:229], v186 offset:59904
	v_add_f32_e32 v192, v192, v36
	v_add_f32_e32 v193, v193, v37
	v_cvt_pk_bf16_f32 v34, v36, v37
	v_exp_f32_e32 v50, v50
	v_exp_f32_e32 v51, v51
	s_waitcnt lgkmcnt(7)
	v_mfma_f32_32x32x16_bf16 v[64:79], v[230:233], v[100:103], v[64:79]
	ds_read_b128 v[230:233], v186 offset:55328
	v_add_f32_e32 v194, v194, v38
	v_add_f32_e32 v195, v195, v39
	v_cvt_pk_bf16_f32 v35, v38, v39
	v_exp_f32_e32 v52, v52
	v_exp_f32_e32 v53, v53
	s_waitcnt lgkmcnt(7)
	v_mfma_f32_32x32x16_bf16 v[206:221], v[234:237], v[100:103], v[206:221]
	ds_read_b128 v[234:237], v186 offset:59936
	v_add_f32_e32 v196, v196, v40
	v_add_f32_e32 v197, v197, v41
	v_cvt_pk_bf16_f32 v36, v40, v41
	v_exp_f32_e32 v54, v54
	v_exp_f32_e32 v55, v55
	s_waitcnt lgkmcnt(7)
	v_mfma_f32_32x32x16_bf16 v[64:79], v[138:141], v[104:107], v[64:79]
	ds_read_b128 v[138:141], v186 offset:55360
	v_add_f32_e32 v198, v198, v42
	v_add_f32_e32 v199, v199, v43
	v_cvt_pk_bf16_f32 v37, v42, v43
	v_exp_f32_e32 v56, v56
	v_exp_f32_e32 v57, v57
	s_waitcnt lgkmcnt(7)
	v_mfma_f32_32x32x16_bf16 v[206:221], v[142:145], v[104:107], v[206:221]
	ds_read_b128 v[142:145], v186 offset:59968
	v_add_f32_e32 v200, v200, v44
	v_add_f32_e32 v201, v201, v45
	v_cvt_pk_bf16_f32 v38, v44, v45
	v_exp_f32_e32 v58, v58
	v_exp_f32_e32 v59, v59
	s_waitcnt lgkmcnt(7)
	v_mfma_f32_32x32x16_bf16 v[64:79], v[162:165], v[108:111], v[64:79]
	ds_read_b128 v[162:165], v186 offset:55392
	v_add_f32_e32 v202, v202, v46
	v_add_f32_e32 v203, v203, v47
	v_cvt_pk_bf16_f32 v39, v46, v47
	v_exp_f32_e32 v60, v60
	v_exp_f32_e32 v61, v61
	s_waitcnt lgkmcnt(7)
	v_mfma_f32_32x32x16_bf16 v[206:221], v[132:135], v[108:111], v[206:221]
	ds_read_b128 v[132:135], v186 offset:60000
	v_add_f32_e32 v188, v188, v48
	v_add_f32_e32 v189, v189, v49
	v_cvt_pk_bf16_f32 v48, v48, v49
	v_add_f32_e32 v190, v190, v50
	v_add_f32_e32 v191, v191, v51
	v_cvt_pk_bf16_f32 v49, v50, v51
	v_exp_f32_e32 v62, v62
	v_exp_f32_e32 v63, v63
	s_waitcnt lgkmcnt(7)
	v_mfma_f32_32x32x16_bf16 v[0:15], v[222:225], v[32:35], v[0:15]
	ds_read_b128 v[222:225], v186
	v_add_f32_e32 v192, v192, v52
	v_add_f32_e32 v193, v193, v53
	v_cvt_pk_bf16_f32 v50, v52, v53
	v_exp_f32_e32 v64, v64
	v_exp_f32_e32 v65, v65
	s_waitcnt lgkmcnt(7)
	v_mfma_f32_32x32x16_bf16 v[16:31], v[226:229], v[32:35], v[16:31]
	ds_read_b128 v[226:229], v186 offset:4608
	v_add_f32_e32 v194, v194, v54
	v_add_f32_e32 v195, v195, v55
	v_cvt_pk_bf16_f32 v51, v54, v55
	v_exp_f32_e32 v66, v66
	v_exp_f32_e32 v67, v67
	s_waitcnt lgkmcnt(7)
	v_mfma_f32_32x32x16_bf16 v[0:15], v[230:233], v[36:39], v[0:15]
	ds_read_b128 v[230:233], v186 offset:32
	v_add_f32_e32 v196, v196, v56
	v_add_f32_e32 v197, v197, v57
	v_cvt_pk_bf16_f32 v52, v56, v57
	v_exp_f32_e32 v68, v68
	v_exp_f32_e32 v69, v69
	s_waitcnt vmcnt(3)
	ds_write_b128 v168, v[80:83] offset:9216
	s_waitcnt vmcnt(2)
	ds_write_b128 v168, v[84:87] offset:18432
	s_waitcnt lgkmcnt(9)
	v_mfma_f32_32x32x16_bf16 v[16:31], v[234:237], v[36:39], v[16:31]
	ds_read_b128 v[234:237], v186 offset:4640
	v_add_f32_e32 v198, v198, v58
	v_add_f32_e32 v199, v199, v59
	v_cvt_pk_bf16_f32 v53, v58, v59
	v_exp_f32_e32 v70, v70
	v_exp_f32_e32 v71, v71
	s_waitcnt vmcnt(1)
	ds_write2_b64 v169, v[88:89], v[90:91] offset1:2
	s_waitcnt vmcnt(0)
	ds_write2_b64 v170, v[92:93], v[94:95] offset0:128 offset1:130
	s_waitcnt lgkmcnt(11)
	v_mfma_f32_32x32x16_bf16 v[0:15], v[138:141], v[48:51], v[0:15]
	ds_read_b128 v[138:141], v186 offset:64
	v_add_f32_e32 v200, v200, v60
	v_add_f32_e32 v201, v201, v61
	v_cvt_pk_bf16_f32 v54, v60, v61
	v_exp_f32_e32 v72, v72
	v_exp_f32_e32 v73, v73
	s_mov_b32 s98, 0xd918000
	v_lshl_add_u64 v[146:147], v[120:121], 0, s[98:99]
	global_load_dwordx4 v[112:115], v[146:147], off offset:2304
	s_mov_b32 s98, 0xd940000
	s_waitcnt lgkmcnt(11)
	v_mfma_f32_32x32x16_bf16 v[16:31], v[142:145], v[48:51], v[16:31]
	ds_read_b128 v[142:145], v186 offset:4672
	v_add_f32_e32 v202, v202, v62
	v_add_f32_e32 v203, v203, v63
	v_cvt_pk_bf16_f32 v55, v62, v63
	v_exp_f32_e32 v74, v74
	v_exp_f32_e32 v75, v75
	v_lshl_add_u64 v[146:147], v[120:121], 0, s[98:99]
	global_load_dwordx4 v[116:119], v[146:147], off offset:2304
	s_mov_b32 s98, 0x17830000
	v_lshl_add_u64 v[146:147], v[124:125], 0, s[98:99]
	s_waitcnt lgkmcnt(11)
	v_mfma_f32_32x32x16_bf16 v[0:15], v[162:165], v[52:55], v[0:15]
	ds_read_b128 v[162:165], v186 offset:96
	v_exp_f32_e32 v76, v76
	v_exp_f32_e32 v77, v77
	global_load_dwordx4 v[120:123], v[146:147], off
	s_mov_b32 s98, 0x17838000
	v_lshl_add_u64 v[146:147], v[124:125], 0, s[98:99]
	global_load_dwordx4 v[124:127], v[146:147], off
	s_waitcnt lgkmcnt(11)
	v_mfma_f32_32x32x16_bf16 v[16:31], v[132:135], v[52:55], v[16:31]
	ds_read_b128 v[132:135], v186 offset:4704
	v_exp_f32_e32 v78, v78
	v_exp_f32_e32 v79, v79
	s_add_i32 s7, s84, 4
	s_waitcnt lgkmcnt(11)
	v_mfma_f32_32x32x16_bf16 v[32:47], v[222:225], v[96:99], 0
	ds_read_b128 v[222:225], v186 offset:64512
	v_add_f32_e32 v188, v188, v64
	v_add_f32_e32 v189, v189, v65
	v_cvt_pk_bf16_f32 v64, v64, v65
	v_add_f32_e32 v190, v190, v66
	v_add_f32_e32 v191, v191, v67
	v_cvt_pk_bf16_f32 v65, v66, v67
	v_exp_f32_e32 v206, v206
	v_exp_f32_e32 v207, v207
	s_waitcnt lgkmcnt(11)
	v_mfma_f32_32x32x16_bf16 v[48:63], v[226:229], v[96:99], 0
	ds_read_b128 v[226:229], v187 offset:32256
	v_add_f32_e32 v192, v192, v68
	v_add_f32_e32 v193, v193, v69
	v_cvt_pk_bf16_f32 v66, v68, v69
	v_exp_f32_e32 v208, v208
	v_exp_f32_e32 v209, v209
	s_waitcnt lgkmcnt(11)
	v_mfma_f32_32x32x16_bf16 v[32:47], v[230:233], v[100:103], v[32:47]
	ds_read_b128 v[230:233], v186 offset:64544
	v_add_f32_e32 v194, v194, v70
	v_add_f32_e32 v195, v195, v71
	v_cvt_pk_bf16_f32 v67, v70, v71
	v_exp_f32_e32 v210, v210
	v_exp_f32_e32 v211, v211
	s_waitcnt lgkmcnt(9)
	v_mfma_f32_32x32x16_bf16 v[48:63], v[234:237], v[100:103], v[48:63]
	ds_read_b128 v[234:237], v187 offset:32288
	v_add_f32_e32 v196, v196, v72
	v_add_f32_e32 v197, v197, v73
	v_cvt_pk_bf16_f32 v68, v72, v73
	v_exp_f32_e32 v212, v212
	v_exp_f32_e32 v213, v213
	s_waitcnt lgkmcnt(7)
	v_mfma_f32_32x32x16_bf16 v[32:47], v[138:141], v[104:107], v[32:47]
	ds_read_b128 v[138:141], v186 offset:64576
	v_add_f32_e32 v198, v198, v74
	v_add_f32_e32 v199, v199, v75
	v_cvt_pk_bf16_f32 v69, v74, v75
	v_exp_f32_e32 v214, v214
	v_exp_f32_e32 v215, v215
	s_waitcnt lgkmcnt(7)
; __device__ __forceinline__ void attn_global(LAS unsigned char* lds, const bf16_t* __restrict__ PROJ, const bf16_t* __restrict__ VT, bf16_t* __restrict__ AO,
;                                             int rowbase, int S, int hq, int q0, float bound2) {
;     ...
;     int t = 0;
; #pragma unroll 1
;     for (; t + 10 < T; t += 4) { ATT_DSTEP(t, 0, true); ATT_DSTEP(t + 2, 2, true); }
; #pragma unroll 1
;     for (; t < T; t += 4) { ATT_DSTEP(t, 0, false); ATT_DSTEP(t + 2, 2, false); }
	v_mfma_f32_32x32x16_bf16 v[48:63], v[142:145], v[104:107], v[48:63]
	ds_read_b128 v[142:145], v187 offset:32320
	v_add_f32_e32 v200, v200, v76
	v_add_f32_e32 v201, v201, v77
	v_cvt_pk_bf16_f32 v70, v76, v77
	v_exp_f32_e32 v216, v216
	v_exp_f32_e32 v217, v217
	s_waitcnt lgkmcnt(7)
	v_mfma_f32_32x32x16_bf16 v[32:47], v[162:165], v[108:111], v[32:47]
	ds_read_b128 v[162:165], v186 offset:64608
	v_add_f32_e32 v202, v202, v78
	v_add_f32_e32 v203, v203, v79
	v_cvt_pk_bf16_f32 v71, v78, v79
	v_exp_f32_e32 v218, v218
	v_exp_f32_e32 v219, v219
	s_waitcnt lgkmcnt(7)
	v_mfma_f32_32x32x16_bf16 v[48:63], v[132:135], v[108:111], v[48:63]
	ds_read_b128 v[132:135], v187 offset:32352
	v_add_f32_e32 v188, v188, v206
	v_add_f32_e32 v189, v189, v207
	v_cvt_pk_bf16_f32 v206, v206, v207
	v_add_f32_e32 v190, v190, v208
	v_add_f32_e32 v191, v191, v209
	v_cvt_pk_bf16_f32 v207, v208, v209
	v_exp_f32_e32 v220, v220
	v_exp_f32_e32 v221, v221
	s_waitcnt lgkmcnt(7)
	v_mfma_f32_32x32x16_bf16 v[0:15], v[222:225], v[64:67], v[0:15]
	v_add_f32_e32 v192, v192, v210
	v_add_f32_e32 v193, v193, v211
	v_cvt_pk_bf16_f32 v208, v210, v211
	v_exp_f32_e32 v32, v32
	v_exp_f32_e32 v33, v33
	s_waitcnt lgkmcnt(6)
	v_mfma_f32_32x32x16_bf16 v[16:31], v[226:229], v[64:67], v[16:31]
	v_add_f32_e32 v194, v194, v212
	v_add_f32_e32 v195, v195, v213
	v_cvt_pk_bf16_f32 v209, v212, v213
	v_exp_f32_e32 v34, v34
	v_exp_f32_e32 v35, v35
	s_waitcnt lgkmcnt(5)
	v_mfma_f32_32x32x16_bf16 v[0:15], v[230:233], v[68:71], v[0:15]
	v_add_f32_e32 v196, v196, v214
	v_add_f32_e32 v197, v197, v215
	v_cvt_pk_bf16_f32 v210, v214, v215
	v_exp_f32_e32 v36, v36
	v_exp_f32_e32 v37, v37
	s_waitcnt lgkmcnt(4)
	v_mfma_f32_32x32x16_bf16 v[16:31], v[234:237], v[68:71], v[16:31]
	s_waitcnt lgkmcnt(0)
	s_barrier
	ds_read_b128 v[222:225], v186 offset:9216
	ds_read_b128 v[226:229], v186 offset:13824
	ds_read_b128 v[230:233], v186 offset:9248
	ds_read_b128 v[234:237], v186 offset:13856
	v_add_f32_e32 v198, v198, v216
	v_add_f32_e32 v199, v199, v217
	v_cvt_pk_bf16_f32 v211, v216, v217
	v_exp_f32_e32 v38, v38
	v_exp_f32_e32 v39, v39
	v_mfma_f32_32x32x16_bf16 v[0:15], v[138:141], v[206:209], v[0:15]
	ds_read_b128 v[138:141], v186 offset:9280
	v_add_f32_e32 v200, v200, v218
	v_add_f32_e32 v201, v201, v219
	v_cvt_pk_bf16_f32 v212, v218, v219
	v_exp_f32_e32 v40, v40
	v_exp_f32_e32 v41, v41
	v_mfma_f32_32x32x16_bf16 v[16:31], v[142:145], v[206:209], v[16:31]
	ds_read_b128 v[142:145], v186 offset:13888
	v_add_f32_e32 v202, v202, v220
	v_add_f32_e32 v203, v203, v221
	v_cvt_pk_bf16_f32 v213, v220, v221
	v_exp_f32_e32 v42, v42
	v_exp_f32_e32 v43, v43
	v_mfma_f32_32x32x16_bf16 v[0:15], v[162:165], v[210:213], v[0:15]
	ds_read_b128 v[162:165], v186 offset:9312
	v_exp_f32_e32 v44, v44
	v_exp_f32_e32 v45, v45
	v_mfma_f32_32x32x16_bf16 v[16:31], v[132:135], v[210:213], v[16:31]
	ds_read_b128 v[132:135], v186 offset:13920
	v_exp_f32_e32 v46, v46
	v_exp_f32_e32 v47, v47
	v_lshl_add_u64 v[158:159], v[158:159], 0, s[26:27]
	v_lshl_add_u64 v[160:161], v[160:161], 0, s[28:29]
	s_sub_u32 s98, s6, 6
	s_cmp_ge_u32 s98, s82
	s_cbranch_scc0 .Lattn_main
	s_mov_b32 s84, s7
	s_waitcnt lgkmcnt(7)
	v_mfma_f32_32x32x16_bf16 v[64:79], v[222:225], v[96:99], 0
	ds_read_b128 v[222:225], v186 offset:36864
	v_add_f32_e32 v188, v188, v32
	v_add_f32_e32 v189, v189, v33
	v_cvt_pk_bf16_f32 v32, v32, v33
	v_add_f32_e32 v190, v190, v34
	v_add_f32_e32 v191, v191, v35
	v_cvt_pk_bf16_f32 v33, v34, v35
	v_exp_f32_e32 v48, v48
	v_exp_f32_e32 v49, v49
	s_waitcnt lgkmcnt(7)
	v_mfma_f32_32x32x16_bf16 v[206:221], v[226:229], v[96:99], 0
	ds_read_b128 v[226:229], v186 offset:41472
	v_add_f32_e32 v192, v192, v36
	v_add_f32_e32 v193, v193, v37
	v_cvt_pk_bf16_f32 v34, v36, v37
	v_exp_f32_e32 v50, v50
	v_exp_f32_e32 v51, v51
	s_waitcnt lgkmcnt(7)
	v_mfma_f32_32x32x16_bf16 v[64:79], v[230:233], v[100:103], v[64:79]
	ds_read_b128 v[230:233], v186 offset:36896
	v_add_f32_e32 v194, v194, v38
	v_add_f32_e32 v195, v195, v39
	v_cvt_pk_bf16_f32 v35, v38, v39
	v_exp_f32_e32 v52, v52
	v_exp_f32_e32 v53, v53
	s_waitcnt lgkmcnt(7)
	v_mfma_f32_32x32x16_bf16 v[206:221], v[234:237], v[100:103], v[206:221]
	ds_read_b128 v[234:237], v186 offset:41504
	v_add_f32_e32 v196, v196, v40
	v_add_f32_e32 v197, v197, v41
	v_cvt_pk_bf16_f32 v36, v40, v41
	v_exp_f32_e32 v54, v54
	v_exp_f32_e32 v55, v55
	s_waitcnt lgkmcnt(7)
	v_mfma_f32_32x32x16_bf16 v[64:79], v[138:141], v[104:107], v[64:79]
	ds_read_b128 v[138:141], v186 offset:36928
	v_add_f32_e32 v198, v198, v42
	v_add_f32_e32 v199, v199, v43
	v_cvt_pk_bf16_f32 v37, v42, v43
	v_exp_f32_e32 v56, v56
	v_exp_f32_e32 v57, v57
	s_waitcnt lgkmcnt(7)
	v_mfma_f32_32x32x16_bf16 v[206:221], v[142:145], v[104:107], v[206:221]
	ds_read_b128 v[142:145], v186 offset:41536
	v_add_f32_e32 v200, v200, v44
	v_add_f32_e32 v201, v201, v45
	v_cvt_pk_bf16_f32 v38, v44, v45
	v_exp_f32_e32 v58, v58
	v_exp_f32_e32 v59, v59
	s_waitcnt lgkmcnt(7)
	v_mfma_f32_32x32x16_bf16 v[64:79], v[162:165], v[108:111], v[64:79]
	ds_read_b128 v[162:165], v186 offset:36960
	v_add_f32_e32 v202, v202, v46
	v_add_f32_e32 v203, v203, v47
	v_cvt_pk_bf16_f32 v39, v46, v47
	v_exp_f32_e32 v60, v60
	v_exp_f32_e32 v61, v61
	s_waitcnt lgkmcnt(7)
	v_mfma_f32_32x32x16_bf16 v[206:221], v[132:135], v[108:111], v[206:221]
	ds_read_b128 v[132:135], v186 offset:41568
	v_add_f32_e32 v188, v188, v48
	v_add_f32_e32 v189, v189, v49
	v_cvt_pk_bf16_f32 v48, v48, v49
	v_add_f32_e32 v190, v190, v50
	v_add_f32_e32 v191, v191, v51
	v_cvt_pk_bf16_f32 v49, v50, v51
	v_exp_f32_e32 v62, v62
	v_exp_f32_e32 v63, v63
	s_waitcnt lgkmcnt(7)
	v_mfma_f32_32x32x16_bf16 v[0:15], v[222:225], v[32:35], v[0:15]
	ds_read_b128 v[222:225], v186 offset:18432
	v_add_f32_e32 v192, v192, v52
	v_add_f32_e32 v193, v193, v53
	v_cvt_pk_bf16_f32 v50, v52, v53
	v_exp_f32_e32 v64, v64
	v_exp_f32_e32 v65, v65
	s_waitcnt lgkmcnt(7)
	v_mfma_f32_32x32x16_bf16 v[16:31], v[226:229], v[32:35], v[16:31]
	ds_read_b128 v[226:229], v186 offset:23040
	v_add_f32_e32 v194, v194, v54
	v_add_f32_e32 v195, v195, v55
	v_cvt_pk_bf16_f32 v51, v54, v55
	v_exp_f32_e32 v66, v66
	v_exp_f32_e32 v67, v67
	s_waitcnt lgkmcnt(7)
	v_mfma_f32_32x32x16_bf16 v[0:15], v[230:233], v[36:39], v[0:15]
	ds_read_b128 v[230:233], v186 offset:18464
	v_add_f32_e32 v196, v196, v56
	v_add_f32_e32 v197, v197, v57
	v_cvt_pk_bf16_f32 v52, v56, v57
	v_exp_f32_e32 v68, v68
	v_exp_f32_e32 v69, v69
	v_add_u32_e32 v204, 0xd800, v136
	v_add_u32_e32 v205, 0xf800, v136
	s_waitcnt vmcnt(3)
	s_waitcnt lgkmcnt(7)
	v_mfma_f32_32x32x16_bf16 v[16:31], v[234:237], v[36:39], v[16:31]
	ds_read_b128 v[234:237], v186 offset:23072
	v_add_f32_e32 v198, v198, v58
	v_add_f32_e32 v199, v199, v59
	v_cvt_pk_bf16_f32 v53, v58, v59
	v_exp_f32_e32 v70, v70
	v_exp_f32_e32 v71, v71
	ds_write_b128 v168, v[112:115] offset:27648
	s_waitcnt vmcnt(2)
	ds_write_b128 v168, v[116:119]
	s_waitcnt lgkmcnt(9)
	v_mfma_f32_32x32x16_bf16 v[0:15], v[138:141], v[48:51], v[0:15]
	ds_read_b128 v[138:141], v186 offset:18496
	v_add_f32_e32 v200, v200, v60
	v_add_f32_e32 v201, v201, v61
	v_cvt_pk_bf16_f32 v54, v60, v61
	v_exp_f32_e32 v72, v72
	v_exp_f32_e32 v73, v73
	s_waitcnt vmcnt(1)
	ds_write2_b64 v204, v[120:121], v[122:123] offset1:2
	s_waitcnt vmcnt(0)
	s_waitcnt lgkmcnt(10)
	v_mfma_f32_32x32x16_bf16 v[16:31], v[142:145], v[48:51], v[16:31]
	ds_read_b128 v[142:145], v186 offset:23104
	v_add_f32_e32 v202, v202, v62
	v_add_f32_e32 v203, v203, v63
	v_cvt_pk_bf16_f32 v55, v62, v63
	v_exp_f32_e32 v74, v74
	v_exp_f32_e32 v75, v75
	ds_write2_b64 v205, v[124:125], v[126:127] offset0:128 offset1:130
	v_lshl_add_u64 v[120:121], v[128:129], 0, v[150:151]
	v_lshl_add_u64 v[124:125], v[130:131], 0, v[150:151]
	s_waitcnt lgkmcnt(11)
	v_mfma_f32_32x32x16_bf16 v[0:15], v[162:165], v[52:55], v[0:15]
	ds_read_b128 v[162:165], v186 offset:18528
	v_exp_f32_e32 v76, v76
	v_exp_f32_e32 v77, v77
	v_lshl_add_u64 v[128:129], v[128:129], 0, s[26:27]
	v_lshl_add_u64 v[130:131], v[130:131], 0, s[28:29]
	s_mov_b32 s14, s8
	s_waitcnt lgkmcnt(11)
	v_mfma_f32_32x32x16_bf16 v[16:31], v[132:135], v[52:55], v[16:31]
	ds_read_b128 v[132:135], v186 offset:23136
	v_exp_f32_e32 v78, v78
	v_exp_f32_e32 v79, v79
	s_add_i32 s6, s6, 4
	s_add_i32 s8, s8, 4
	s_waitcnt lgkmcnt(11)
	v_mfma_f32_32x32x16_bf16 v[32:47], v[222:225], v[96:99], 0
	ds_read_b128 v[222:225], v186 offset:46080
	v_add_f32_e32 v188, v188, v64
	v_add_f32_e32 v189, v189, v65
	v_cvt_pk_bf16_f32 v64, v64, v65
	v_add_f32_e32 v190, v190, v66
	v_add_f32_e32 v191, v191, v67
	v_cvt_pk_bf16_f32 v65, v66, v67
	v_exp_f32_e32 v206, v206
	v_exp_f32_e32 v207, v207
	s_waitcnt lgkmcnt(11)
	v_mfma_f32_32x32x16_bf16 v[48:63], v[226:229], v[96:99], 0
	ds_read_b128 v[226:229], v186 offset:50688
	v_add_f32_e32 v192, v192, v68
	v_add_f32_e32 v193, v193, v69
	v_cvt_pk_bf16_f32 v66, v68, v69
	v_exp_f32_e32 v208, v208
	v_exp_f32_e32 v209, v209
	s_waitcnt lgkmcnt(11)
	v_mfma_f32_32x32x16_bf16 v[32:47], v[230:233], v[100:103], v[32:47]
	ds_read_b128 v[230:233], v186 offset:46112
	v_add_f32_e32 v194, v194, v70
	v_add_f32_e32 v195, v195, v71
	v_cvt_pk_bf16_f32 v67, v70, v71
	v_exp_f32_e32 v210, v210
	v_exp_f32_e32 v211, v211
	s_waitcnt lgkmcnt(11)
	v_mfma_f32_32x32x16_bf16 v[48:63], v[234:237], v[100:103], v[48:63]
	ds_read_b128 v[234:237], v186 offset:50720
	v_add_f32_e32 v196, v196, v72
	v_add_f32_e32 v197, v197, v73
	v_cvt_pk_bf16_f32 v68, v72, v73
	v_exp_f32_e32 v212, v212
	v_exp_f32_e32 v213, v213
	s_waitcnt lgkmcnt(9)
	v_mfma_f32_32x32x16_bf16 v[32:47], v[138:141], v[104:107], v[32:47]
	ds_read_b128 v[138:141], v186 offset:46144
	v_add_f32_e32 v198, v198, v74
	v_add_f32_e32 v199, v199, v75
	v_cvt_pk_bf16_f32 v69, v74, v75
	v_exp_f32_e32 v214, v214
	v_exp_f32_e32 v215, v215
	s_waitcnt lgkmcnt(8)
	v_mfma_f32_32x32x16_bf16 v[48:63], v[142:145], v[104:107], v[48:63]
	ds_read_b128 v[142:145], v186 offset:50752
	v_add_f32_e32 v200, v200, v76
	v_add_f32_e32 v201, v201, v77
	v_cvt_pk_bf16_f32 v70, v76, v77
	v_exp_f32_e32 v216, v216
	v_exp_f32_e32 v217, v217
	s_waitcnt lgkmcnt(7)
	v_mfma_f32_32x32x16_bf16 v[32:47], v[162:165], v[108:111], v[32:47]
	ds_read_b128 v[162:165], v186 offset:46176
	v_add_f32_e32 v202, v202, v78
	v_add_f32_e32 v203, v203, v79
	v_cvt_pk_bf16_f32 v71, v78, v79
	v_exp_f32_e32 v218, v218
	v_exp_f32_e32 v219, v219
	s_waitcnt lgkmcnt(7)
	v_mfma_f32_32x32x16_bf16 v[48:63], v[132:135], v[108:111], v[48:63]
	ds_read_b128 v[132:135], v186 offset:50784
	v_add_f32_e32 v188, v188, v206
	v_add_f32_e32 v189, v189, v207
	v_cvt_pk_bf16_f32 v206, v206, v207
	v_add_f32_e32 v190, v190, v208
	v_add_f32_e32 v191, v191, v209
	v_cvt_pk_bf16_f32 v207, v208, v209
	v_exp_f32_e32 v220, v220
	v_exp_f32_e32 v221, v221
	s_waitcnt lgkmcnt(7)
	v_mfma_f32_32x32x16_bf16 v[0:15], v[222:225], v[64:67], v[0:15]
	v_add_f32_e32 v192, v192, v210
	v_add_f32_e32 v193, v193, v211
	v_cvt_pk_bf16_f32 v208, v210, v211
	v_exp_f32_e32 v32, v32
	v_exp_f32_e32 v33, v33
	s_waitcnt lgkmcnt(6)
	v_mfma_f32_32x32x16_bf16 v[16:31], v[226:229], v[64:67], v[16:31]
	v_add_f32_e32 v194, v194, v212
	v_add_f32_e32 v195, v195, v213
	v_cvt_pk_bf16_f32 v209, v212, v213
	v_exp_f32_e32 v34, v34
	v_exp_f32_e32 v35, v35
	s_waitcnt lgkmcnt(5)
	v_mfma_f32_32x32x16_bf16 v[0:15], v[230:233], v[68:71], v[0:15]
	v_add_f32_e32 v196, v196, v214
	v_add_f32_e32 v197, v197, v215
	v_cvt_pk_bf16_f32 v210, v214, v215
	v_exp_f32_e32 v36, v36
	v_exp_f32_e32 v37, v37
	s_waitcnt lgkmcnt(4)
	v_mfma_f32_32x32x16_bf16 v[16:31], v[234:237], v[68:71], v[16:31]
	s_waitcnt lgkmcnt(0)
	s_barrier
	ds_read_b128 v[222:225], v186 offset:27648
	ds_read_b128 v[226:229], v186 offset:32256
	ds_read_b128 v[230:233], v186 offset:27680
	ds_read_b128 v[234:237], v186 offset:32288
	v_add_f32_e32 v198, v198, v216
	v_add_f32_e32 v199, v199, v217
	v_cvt_pk_bf16_f32 v211, v216, v217
	v_exp_f32_e32 v38, v38
	v_exp_f32_e32 v39, v39
	v_mfma_f32_32x32x16_bf16 v[0:15], v[138:141], v[206:209], v[0:15]
	ds_read_b128 v[138:141], v186 offset:27712
	v_add_f32_e32 v200, v200, v218
	v_add_f32_e32 v201, v201, v219
	v_cvt_pk_bf16_f32 v212, v218, v219
	v_exp_f32_e32 v40, v40
	v_exp_f32_e32 v41, v41
	v_mfma_f32_32x32x16_bf16 v[16:31], v[142:145], v[206:209], v[16:31]
	ds_read_b128 v[142:145], v186 offset:32320
	v_add_f32_e32 v202, v202, v220
	v_add_f32_e32 v203, v203, v221
	v_cvt_pk_bf16_f32 v213, v220, v221
	v_exp_f32_e32 v42, v42
	v_exp_f32_e32 v43, v43
	v_mfma_f32_32x32x16_bf16 v[0:15], v[162:165], v[210:213], v[0:15]
	ds_read_b128 v[162:165], v186 offset:27744
	v_exp_f32_e32 v44, v44
	v_exp_f32_e32 v45, v45
	v_mfma_f32_32x32x16_bf16 v[16:31], v[132:135], v[210:213], v[16:31]
	ds_read_b128 v[132:135], v186 offset:32352
	v_exp_f32_e32 v46, v46
	v_exp_f32_e32 v47, v47
	s_waitcnt lgkmcnt(7)
	v_mfma_f32_32x32x16_bf16 v[64:79], v[222:225], v[96:99], 0
	ds_read_b128 v[222:225], v186 offset:55296
	v_add_f32_e32 v188, v188, v32
	v_add_f32_e32 v189, v189, v33
	v_cvt_pk_bf16_f32 v32, v32, v33
	v_add_f32_e32 v190, v190, v34
	v_add_f32_e32 v191, v191, v35
	v_cvt_pk_bf16_f32 v33, v34, v35
	v_exp_f32_e32 v48, v48
	v_exp_f32_e32 v49, v49
	s_waitcnt lgkmcnt(7)
	v_mfma_f32_32x32x16_bf16 v[206:221], v[226:229], v[96:99], 0
	ds_read_b128 v[226:229], v186 offset:59904
	v_add_f32_e32 v192, v192, v36
	v_add_f32_e32 v193, v193, v37
	v_cvt_pk_bf16_f32 v34, v36, v37
	v_exp_f32_e32 v50, v50
	v_exp_f32_e32 v51, v51
	s_waitcnt lgkmcnt(7)
	v_mfma_f32_32x32x16_bf16 v[64:79], v[230:233], v[100:103], v[64:79]
	ds_read_b128 v[230:233], v186 offset:55328
	v_add_f32_e32 v194, v194, v38
	v_add_f32_e32 v195, v195, v39
	v_cvt_pk_bf16_f32 v35, v38, v39
	v_exp_f32_e32 v52, v52
	v_exp_f32_e32 v53, v53
	s_waitcnt lgkmcnt(7)
	v_mfma_f32_32x32x16_bf16 v[206:221], v[234:237], v[100:103], v[206:221]
	ds_read_b128 v[234:237], v186 offset:59936
	v_add_f32_e32 v196, v196, v40
	v_add_f32_e32 v197, v197, v41
	v_cvt_pk_bf16_f32 v36, v40, v41
	v_exp_f32_e32 v54, v54
	v_exp_f32_e32 v55, v55
	s_waitcnt lgkmcnt(7)
	v_mfma_f32_32x32x16_bf16 v[64:79], v[138:141], v[104:107], v[64:79]
	ds_read_b128 v[138:141], v186 offset:55360
	v_add_f32_e32 v198, v198, v42
	v_add_f32_e32 v199, v199, v43
	v_cvt_pk_bf16_f32 v37, v42, v43
	v_exp_f32_e32 v56, v56
	v_exp_f32_e32 v57, v57
	s_waitcnt lgkmcnt(7)
	v_mfma_f32_32x32x16_bf16 v[206:221], v[142:145], v[104:107], v[206:221]
	ds_read_b128 v[142:145], v186 offset:59968
	v_add_f32_e32 v200, v200, v44
	v_add_f32_e32 v201, v201, v45
	v_cvt_pk_bf16_f32 v38, v44, v45
	v_exp_f32_e32 v58, v58
	v_exp_f32_e32 v59, v59
	s_waitcnt lgkmcnt(7)
	v_mfma_f32_32x32x16_bf16 v[64:79], v[162:165], v[108:111], v[64:79]
	ds_read_b128 v[162:165], v186 offset:55392
	v_add_f32_e32 v202, v202, v46
	v_add_f32_e32 v203, v203, v47
	v_cvt_pk_bf16_f32 v39, v46, v47
	v_exp_f32_e32 v60, v60
	v_exp_f32_e32 v61, v61
	s_waitcnt lgkmcnt(7)
	v_mfma_f32_32x32x16_bf16 v[206:221], v[132:135], v[108:111], v[206:221]
	ds_read_b128 v[132:135], v186 offset:60000
	v_add_f32_e32 v188, v188, v48
	v_add_f32_e32 v189, v189, v49
	v_cvt_pk_bf16_f32 v48, v48, v49
	v_add_f32_e32 v190, v190, v50
	v_add_f32_e32 v191, v191, v51
	v_cvt_pk_bf16_f32 v49, v50, v51
	v_exp_f32_e32 v62, v62
	v_exp_f32_e32 v63, v63
	s_waitcnt lgkmcnt(7)
	v_mfma_f32_32x32x16_bf16 v[0:15], v[222:225], v[32:35], v[0:15]
	v_add_f32_e32 v192, v192, v52
	v_add_f32_e32 v193, v193, v53
	v_cvt_pk_bf16_f32 v50, v52, v53
	v_exp_f32_e32 v64, v64
	v_exp_f32_e32 v65, v65
	s_waitcnt lgkmcnt(6)
	v_mfma_f32_32x32x16_bf16 v[16:31], v[226:229], v[32:35], v[16:31]
	v_add_f32_e32 v194, v194, v54
	v_add_f32_e32 v195, v195, v55
	v_cvt_pk_bf16_f32 v51, v54, v55
	v_exp_f32_e32 v66, v66
	v_exp_f32_e32 v67, v67
	s_waitcnt lgkmcnt(5)
	v_mfma_f32_32x32x16_bf16 v[0:15], v[230:233], v[36:39], v[0:15]
	v_add_f32_e32 v196, v196, v56
	v_add_f32_e32 v197, v197, v57
	v_cvt_pk_bf16_f32 v52, v56, v57
	v_exp_f32_e32 v68, v68
	v_exp_f32_e32 v69, v69
	s_waitcnt lgkmcnt(4)
	v_mfma_f32_32x32x16_bf16 v[16:31], v[234:237], v[36:39], v[16:31]
	v_add_f32_e32 v198, v198, v58
	v_add_f32_e32 v199, v199, v59
	v_cvt_pk_bf16_f32 v53, v58, v59
	v_exp_f32_e32 v70, v70
	v_exp_f32_e32 v71, v71
	s_waitcnt lgkmcnt(3)
	v_mfma_f32_32x32x16_bf16 v[0:15], v[138:141], v[48:51], v[0:15]
	v_add_f32_e32 v200, v200, v60
	v_add_f32_e32 v201, v201, v61
	v_cvt_pk_bf16_f32 v54, v60, v61
	v_exp_f32_e32 v72, v72
	v_exp_f32_e32 v73, v73
	s_waitcnt lgkmcnt(2)
	v_mfma_f32_32x32x16_bf16 v[16:31], v[142:145], v[48:51], v[16:31]
	v_add_f32_e32 v202, v202, v62
	v_add_f32_e32 v203, v203, v63
	v_cvt_pk_bf16_f32 v55, v62, v63
	v_exp_f32_e32 v74, v74
	v_exp_f32_e32 v75, v75
	s_waitcnt lgkmcnt(1)
	v_mfma_f32_32x32x16_bf16 v[0:15], v[162:165], v[52:55], v[0:15]
	v_exp_f32_e32 v76, v76
	v_exp_f32_e32 v77, v77
	s_waitcnt lgkmcnt(0)
	v_mfma_f32_32x32x16_bf16 v[16:31], v[132:135], v[52:55], v[16:31]
	v_exp_f32_e32 v78, v78
	v_exp_f32_e32 v79, v79
	s_add_i32 s7, s84, 4
	ds_read_b128 v[222:225], v186 offset:64512
	v_add_f32_e32 v188, v188, v64
	v_add_f32_e32 v189, v189, v65
	v_cvt_pk_bf16_f32 v64, v64, v65
	v_add_f32_e32 v190, v190, v66
	v_add_f32_e32 v191, v191, v67
	v_cvt_pk_bf16_f32 v65, v66, v67
	v_exp_f32_e32 v206, v206
	v_exp_f32_e32 v207, v207
	ds_read_b128 v[226:229], v187 offset:32256
	v_add_f32_e32 v192, v192, v68
	v_add_f32_e32 v193, v193, v69
	v_cvt_pk_bf16_f32 v66, v68, v69
	v_exp_f32_e32 v208, v208
	v_exp_f32_e32 v209, v209
	ds_read_b128 v[230:233], v186 offset:64544
	v_add_f32_e32 v194, v194, v70
	v_add_f32_e32 v195, v195, v71
	v_cvt_pk_bf16_f32 v67, v70, v71
	v_exp_f32_e32 v210, v210
	v_exp_f32_e32 v211, v211
	ds_read_b128 v[234:237], v187 offset:32288
	v_add_f32_e32 v196, v196, v72
	v_add_f32_e32 v197, v197, v73
	v_cvt_pk_bf16_f32 v68, v72, v73
	v_exp_f32_e32 v212, v212
	v_exp_f32_e32 v213, v213
	ds_read_b128 v[138:141], v186 offset:64576
	v_add_f32_e32 v198, v198, v74
	v_add_f32_e32 v199, v199, v75
	v_cvt_pk_bf16_f32 v69, v74, v75
	v_exp_f32_e32 v214, v214
	v_exp_f32_e32 v215, v215
	ds_read_b128 v[142:145], v187 offset:32320
	v_add_f32_e32 v200, v200, v76
	v_add_f32_e32 v201, v201, v77
	v_cvt_pk_bf16_f32 v70, v76, v77
	v_exp_f32_e32 v216, v216
	v_exp_f32_e32 v217, v217
	ds_read_b128 v[162:165], v186 offset:64608
	v_add_f32_e32 v202, v202, v78
	v_add_f32_e32 v203, v203, v79
	v_cvt_pk_bf16_f32 v71, v78, v79
	v_exp_f32_e32 v218, v218
	v_exp_f32_e32 v219, v219
	ds_read_b128 v[132:135], v187 offset:32352
	v_add_f32_e32 v188, v188, v206
	v_add_f32_e32 v189, v189, v207
	v_cvt_pk_bf16_f32 v206, v206, v207
	v_add_f32_e32 v190, v190, v208
	v_add_f32_e32 v191, v191, v209
	v_cvt_pk_bf16_f32 v207, v208, v209
	v_exp_f32_e32 v220, v220
	v_exp_f32_e32 v221, v221
	s_waitcnt lgkmcnt(7)
	v_mfma_f32_32x32x16_bf16 v[0:15], v[222:225], v[64:67], v[0:15]
	v_add_f32_e32 v192, v192, v210
	v_add_f32_e32 v193, v193, v211
	v_cvt_pk_bf16_f32 v208, v210, v211
	s_nop 0
	s_nop 0
	s_waitcnt lgkmcnt(6)
	v_mfma_f32_32x32x16_bf16 v[16:31], v[226:229], v[64:67], v[16:31]
	v_add_f32_e32 v194, v194, v212
	v_add_f32_e32 v195, v195, v213
	v_cvt_pk_bf16_f32 v209, v212, v213
	s_nop 0
	s_nop 0
	s_waitcnt lgkmcnt(5)
	v_mfma_f32_32x32x16_bf16 v[0:15], v[230:233], v[68:71], v[0:15]
	v_add_f32_e32 v196, v196, v214
	v_add_f32_e32 v197, v197, v215
	v_cvt_pk_bf16_f32 v210, v214, v215
	s_nop 0
	s_nop 0
	s_waitcnt lgkmcnt(4)
	v_mfma_f32_32x32x16_bf16 v[16:31], v[234:237], v[68:71], v[16:31]
	s_waitcnt lgkmcnt(0)
	s_barrier
	v_add_f32_e32 v198, v198, v216
	v_add_f32_e32 v199, v199, v217
	v_cvt_pk_bf16_f32 v211, v216, v217
	s_nop 0
	s_nop 0
	v_mfma_f32_32x32x16_bf16 v[0:15], v[138:141], v[206:209], v[0:15]
	v_add_f32_e32 v200, v200, v218
	v_add_f32_e32 v201, v201, v219
	v_cvt_pk_bf16_f32 v212, v218, v219
	s_nop 0
	s_nop 0
	v_mfma_f32_32x32x16_bf16 v[16:31], v[142:145], v[206:209], v[16:31]
	v_add_f32_e32 v202, v202, v220
	v_add_f32_e32 v203, v203, v221
	v_cvt_pk_bf16_f32 v213, v220, v221
	s_nop 0
	s_nop 0
	v_mfma_f32_32x32x16_bf16 v[0:15], v[162:165], v[210:213], v[0:15]
	v_mfma_f32_32x32x16_bf16 v[16:31], v[132:135], v[210:213], v[16:31]
